# ws_unit cooperative LDS ring + anti-phase halves; sb_unit hand-written, head-major unit order
# baseline (speedup 1.0000x reference)
.LBB0_215:
	s_or_b64 exec, exec, s[0:1]
	v_readlane_b32 s0, v254, 54
	s_waitcnt vmcnt(0) lgkmcnt(0)
	s_barrier
	v_mov_b32_e32 v0, s0
	ds_read_b32 v0, v0
	s_mov_b64 s[0:1], -1
	s_waitcnt lgkmcnt(0)
	v_cmp_lt_i32_e32 vcc, 63, v0
	v_readfirstlane_b32 s2, v0
	s_cbranch_vccnz .LBB0_210
	s_and_b32 s3, s2, 1
	s_lshl_b32 s0, s3, 2
	s_add_i32 s40, s0, s20
	s_and_b32 s0, s2, -2
	s_sub_i32 s39, 63, s0
	s_sub_i32 s41, s39, s21
	s_lshl_b32 s35, s41, 5
	v_readlane_b32 s0, v253, 31
	s_mul_i32 s38, s40, 0x2980
	v_and_b32_e32 v149, 31, v186
	v_bfe_u32 v147, v186, 5, 1
	s_or_b32 s2, s3, s0
	v_or_b32_e32 v150, s35, v149
	s_lshl_b32 s1, s0, 10
	v_add_u32_e32 v151, s1, v150
	s_lshl_b32 s1, s2, 13
	s_add_u32 s16, s28, s1
	s_addc_u32 s17, s29, 0
	v_lshlrev_b32_e32 v152, 2, v150
	global_load_dword v140, v152, s[16:17]
	s_sub_i32 s1, s39, 1
	s_lshl_b32 s1, s1, 7
	v_and_b32_e32 v144, 63, v186
	v_lshl_add_u32 v155, v144, 2, s1
	global_load_dword v100, v155, s[16:17]
	v_lshlrev_b32_e32 v153, 10, v151
	v_lshl_add_u32 v153, v147, 4, v153
	s_lshl_b32 s1, s40, 7
	s_add_u32 s16, s10, s1
	s_addc_u32 s17, s11, 0
	global_load_dwordx4 v[48:51], v153, s[16:17]
	global_load_dwordx4 v[52:55], v153, s[16:17] offset:32
	global_load_dwordx4 v[56:59], v153, s[16:17] offset:64
	global_load_dwordx4 v[60:63], v153, s[16:17] offset:96
	v_mul_u32_u24_e32 v154, s66, v151
	s_mul_i32 s1, s40, 6
	v_add_u32_e32 v154, s1, v154
	global_load_dword v141, v154, s[12:13] offset:2
	v_lshlrev_b32_e32 v144, 4, v144
	v_lshlrev_b32_e32 v145, 5, v149
	v_lshl_add_u32 v145, v147, 4, v145
	s_lshl_b32 s0, s2, 18
	s_lshl_b32 s1, s20, 10
	s_add_u32 s0, s0, s1
	s_cmp_eq_u32 s21, 0
	s_cselect_b32 s16, s22, s26
	s_cselect_b32 s17, s23, s27
	s_cselect_b32 s18, s30, s24
	s_cselect_b32 s3, s31, s25
	s_cselect_b64 vcc, -1, 0
	s_add_u32 s42, s16, s0
	s_addc_u32 s43, s17, 0
	s_add_u32 s44, s18, s0
	s_addc_u32 s45, s3, 0
	v_cndmask_b32_e32 v98, v145, v144, vcc
	s_lshl_b32 s0, s21, 2
	s_add_i32 s0, s0, s20
	s_lshl_b32 s0, s0, 10
	s_add_i32 s36, s0, 0x15000
	s_sub_i32 s14, s39, 17
	s_max_i32 s14, s14, 0
	s_mov_b32 s46, 0
	s_mov_b32 s47, s14
	s_mov_b32 s49, 0
	s_mov_b32 s15, 0
	s_mov_b32 s48, 0
	s_lshl_b32 s16, s47, 12
	s_cmp_eq_u32 s46, 0
	s_cselect_b32 s0, s42, s44
	s_cselect_b32 s1, s43, s45
	s_add_u32 s0, s0, s16
	s_addc_u32 s1, s1, 0
	s_and_b32 s16, s49, 7
	s_lshl_b32 s16, s16, 13
	s_add_i32 m0, s16, s36
	s_add_i32 s49, s49, 1
	global_load_lds_dwordx4 v98, s[0:1]
	s_cmp_eq_u32 s46, 0
	s_cbranch_scc0 .Lws_ga1_sel
	s_add_i32 s47, s47, 1
	s_cmp_le_i32 s47, s39
	s_cbranch_scc1 .Lws_ga1_done
	s_mov_b32 s46, 1
	s_branch .Lws_ga1_blk
.Lws_ga1_sel:
	s_bitcmp0_b32 s47, 0
	s_cbranch_scc0 .Lws_ga1_odd
	s_add_i32 s47, s47, 1
	s_branch .Lws_ga1_done
.Lws_ga1_odd:
	s_cmp_eq_u32 s48, 0
	s_cbranch_scc1 .Lws_ga1_done
.Lws_ga1_blk:
	s_ff1_i32_b32 s16, s48
	s_lshl_b32 s47, s16, 1
	s_add_i32 s16, s48, -1
	s_and_b32 s48, s48, s16
.Lws_ga1_done:
	s_lshl_b32 s16, s47, 12
	s_cmp_eq_u32 s46, 0
	s_cselect_b32 s0, s42, s44
	s_cselect_b32 s1, s43, s45
	s_add_u32 s0, s0, s16
	s_addc_u32 s1, s1, 0
	s_and_b32 s16, s49, 7
	s_lshl_b32 s16, s16, 13
	s_add_i32 m0, s16, s36
	s_add_i32 s49, s49, 1
	global_load_lds_dwordx4 v98, s[0:1]
	v_lshlrev_b32_e32 v146, 2, v147
	v_sub_u32_e32 v146, v150, v146
	v_add_u32_e32 v146, 5, v146
	v_lshlrev_b32_e32 v146, 2, v146
	v_mov_b32_e32 v157, s38
	v_xor_b32_e32 v148, 32, v190
	v_lshlrev_b32_e32 v148, 2, v148
	v_lshlrev_b32_e32 v156, 13, v151
	v_lshl_add_u32 v156, v147, 4, v156
	v_mov_b32_e32 v138, 0
	v_mov_b32_e32 v202, 0
	v_mov_b32_e32 v203, 0
	v_mov_b32_e32 v204, 0
	v_mov_b32_e32 v205, 0
	v_mov_b32_e32 v206, 0
	v_mov_b32_e32 v207, 0
	v_mov_b32_e32 v208, 0
	v_mov_b32_e32 v209, 0
	v_mov_b32_e32 v210, 0
	v_mov_b32_e32 v211, 0
	v_mov_b32_e32 v212, 0
	v_mov_b32_e32 v213, 0
	v_mov_b32_e32 v214, 0
	v_mov_b32_e32 v215, 0
	v_mov_b32_e32 v216, 0
	v_mov_b32_e32 v217, 0
	v_mov_b32_e32 v218, 0
	v_mov_b32_e32 v219, 0
	v_mov_b32_e32 v220, 0
	v_mov_b32_e32 v221, 0
	v_mov_b32_e32 v222, 0
	v_mov_b32_e32 v223, 0
	v_mov_b32_e32 v224, 0
	v_mov_b32_e32 v225, 0
	v_mov_b32_e32 v226, 0
	v_mov_b32_e32 v227, 0
	v_mov_b32_e32 v228, 0
	v_mov_b32_e32 v229, 0
	v_mov_b32_e32 v230, 0
	v_mov_b32_e32 v231, 0
	v_mov_b32_e32 v232, 0
	v_mov_b32_e32 v233, 0
	s_lshl_b32 s17, s14, 7
	s_sub_i32 s17, 0x2080, s17
	s_sub_i32 s18, s41, 16
	s_cmp_ge_i32 s14, s18
	s_cselect_b32 s18, 1, 0
	s_cmp_le_i32 s14, s41
	s_cselect_b32 s16, 1, 0
	s_and_b32 s16, s16, s18
	v_add_u32_e32 v152, s17, v146
	v_mad_u32_u24 v139, s16, v152, v157
	ds_read2_b32 v[236:237], v139 offset0:27 offset1:26
	ds_read2_b32 v[238:239], v139 offset0:25 offset1:24
	ds_read2_b32 v[240:241], v139 offset0:19 offset1:18
	ds_read2_b32 v[242:243], v139 offset0:17 offset1:16
	ds_read2_b32 v[244:245], v139 offset0:11 offset1:10
	ds_read2_b32 v[246:247], v139 offset0:9 offset1:8
	ds_read2_b32 v[248:249], v139 offset0:3 offset1:2
	ds_read2_b32 v[250:251], v139 offset0:1 offset1:0
	v_mov_b32_e32 v130, 0
	v_mov_b32_e32 v131, 0
	v_mov_b32_e32 v132, 0
	v_mov_b32_e32 v133, 0
	v_mov_b32_e32 v134, 0
	v_mov_b32_e32 v135, 0
	v_mov_b32_e32 v136, 0
	v_mov_b32_e32 v137, 0
	v_mov_b32_e32 v82, 0
	v_mov_b32_e32 v83, 0
	v_mov_b32_e32 v84, 0
	v_mov_b32_e32 v85, 0
	v_mov_b32_e32 v86, 0
	v_mov_b32_e32 v87, 0
	v_mov_b32_e32 v88, 0
	v_mov_b32_e32 v89, 0
	v_mov_b32_e32 v90, 0
	v_mov_b32_e32 v91, 0
	v_mov_b32_e32 v92, 0
	v_mov_b32_e32 v93, 0
	v_mov_b32_e32 v94, 0
	v_mov_b32_e32 v95, 0
	v_mov_b32_e32 v96, 0
	v_mov_b32_e32 v97, 0
	s_waitcnt vmcnt(2)
	v_xor_b32_e32 v153, 1, v190
	v_lshlrev_b32_e32 v153, 2, v153
	ds_bpermute_b32 v154, v153, v100
	s_waitcnt lgkmcnt(0)
	v_or_b32_e32 v100, v100, v154
	v_xor_b32_e32 v153, 2, v190
	v_lshlrev_b32_e32 v153, 2, v153
	ds_bpermute_b32 v154, v153, v100
	s_waitcnt lgkmcnt(0)
	v_or_b32_e32 v100, v100, v154
	v_xor_b32_e32 v153, 4, v190
	v_lshlrev_b32_e32 v153, 2, v153
	ds_bpermute_b32 v154, v153, v100
	s_waitcnt lgkmcnt(0)
	v_or_b32_e32 v100, v100, v154
	v_xor_b32_e32 v153, 8, v190
	v_lshlrev_b32_e32 v153, 2, v153
	ds_bpermute_b32 v154, v153, v100
	s_waitcnt lgkmcnt(0)
	v_or_b32_e32 v100, v100, v154
	v_xor_b32_e32 v153, 16, v190
	v_lshlrev_b32_e32 v153, 2, v153
	ds_bpermute_b32 v154, v153, v100
	s_waitcnt lgkmcnt(0)
	v_or_b32_e32 v100, v100, v154
	v_xor_b32_e32 v153, 32, v190
	v_lshlrev_b32_e32 v153, 2, v153
	ds_bpermute_b32 v154, v153, v100
	s_waitcnt lgkmcnt(0)
	v_or_b32_e32 v100, v100, v154
	s_nop 1
	v_readfirstlane_b32 s0, v100
	s_nop 3
	s_or_b32 s0, s0, 1
	s_mov_b32 s48, s0
	s_mov_b32 s19, s0
	s_cmp_eq_u32 s46, 0
	s_cbranch_scc0 .Lws_ga2_sel
	s_add_i32 s47, s47, 1
	s_cmp_le_i32 s47, s39
	s_cbranch_scc1 .Lws_ga2_done
	s_mov_b32 s46, 1
	s_branch .Lws_ga2_blk

.Lws_ga2_done:
	s_lshl_b32 s16, s47, 12
	s_cmp_eq_u32 s46, 0
	s_cselect_b32 s0, s42, s44
	s_cselect_b32 s1, s43, s45
	s_add_u32 s0, s0, s16
	s_addc_u32 s1, s1, 0
	s_and_b32 s16, s49, 7
	s_lshl_b32 s16, s16, 13
	s_add_i32 m0, s16, s36
	s_add_i32 s49, s49, 1
	global_load_lds_dwordx4 v98, s[0:1]
	s_cmp_eq_u32 s46, 0
	s_cbranch_scc0 .Lws_ga3_sel
	s_add_i32 s47, s47, 1
	s_cmp_le_i32 s47, s39
	s_cbranch_scc1 .Lws_ga3_done
	s_mov_b32 s46, 1
	s_branch .Lws_ga3_blk

.Lws_ga6_done:
	s_lshl_b32 s16, s47, 12
	s_cmp_eq_u32 s46, 0
	s_cselect_b32 s0, s42, s44
	s_cselect_b32 s1, s43, s45
	s_add_u32 s0, s0, s16
	s_addc_u32 s1, s1, 0
	s_and_b32 s16, s49, 7
	s_lshl_b32 s16, s16, 13
	s_add_i32 m0, s16, s36
	s_add_i32 s49, s49, 1
	global_load_lds_dwordx4 v98, s[0:1]
	s_waitcnt vmcnt(5)
	s_barrier
	s_add_i32 s16, s15, 0
	s_and_b32 s16, s16, 7
	s_lshl_b32 s16, s16, 13
	s_add_i32 s16, s16, 0x15000
	v_add_u32_e32 v101, s16, v144
	ds_read_b128 v[66:69], v101
	ds_read_b128 v[70:73], v101 offset:1024
	ds_read_b128 v[74:77], v101 offset:2048
	ds_read_b128 v[78:81], v101 offset:3072
	s_waitcnt lgkmcnt(0)
	s_cmp_eq_u32 s21, 0
	s_cbranch_scc1 .Lws_skew0
	s_barrier
.Lws_skew0:
.Lws_wloop:
	v_mfma_f32_32x32x16_bf16 v[202:217], v[82:85], v[130:133], v[202:217]
	v_mfma_f32_32x32x16_bf16 v[218:233], v[86:89], v[130:133], v[218:233]
	v_mfma_f32_32x32x16_bf16 v[202:217], v[90:93], v[134:137], v[202:217]
	v_mfma_f32_32x32x16_bf16 v[218:233], v[94:97], v[134:137], v[218:233]
	s_add_i32 s16, s15, 0
	s_and_b32 s16, s16, 7
	s_lshl_b32 s16, s16, 13
	s_add_i32 s16, s16, 0x15000
	v_add_u32_e32 v99, s16, v144
	ds_read_b128 v[82:85], v99 offset:4096
	ds_read_b128 v[86:89], v99 offset:5120
	ds_read_b128 v[90:93], v99 offset:6144
	ds_read_b128 v[94:97], v99 offset:7168
	v_mfma_f32_32x32x16_bf16 v[32:47], v[66:69], v[48:51], v[236:251]
	v_mfma_f32_32x32x16_bf16 v[32:47], v[70:73], v[52:55], v[32:47]
	v_mfma_f32_32x32x16_bf16 v[32:47], v[74:77], v[56:59], v[32:47]
	v_mfma_f32_32x32x16_bf16 v[32:47], v[78:81], v[60:63], v[32:47]
	s_add_i32 s16, s15, 1
	s_and_b32 s16, s16, 7
	s_lshl_b32 s16, s16, 13
	s_add_i32 s16, s16, 0x15000
	v_add_u32_e32 v101, s16, v144
	ds_read_b128 v[66:69], v101
	ds_read_b128 v[70:73], v101 offset:1024
	ds_read_b128 v[74:77], v101 offset:2048
	ds_read_b128 v[78:81], v101 offset:3072
	s_cmp_eq_u32 s46, 0
	s_cbranch_scc0 .Lws_ga7_sel
	s_add_i32 s47, s47, 1
	s_cmp_le_i32 s47, s39
	s_cbranch_scc1 .Lws_ga7_done
	s_mov_b32 s46, 1
	s_branch .Lws_ga7_blk

.Lws_ga7_done:
	s_lshl_b32 s16, s47, 12
	s_cmp_eq_u32 s46, 0
	s_cselect_b32 s0, s42, s44
	s_cselect_b32 s1, s43, s45
	s_add_u32 s0, s0, s16
	s_addc_u32 s1, s1, 0
	s_and_b32 s16, s49, 7
	s_lshl_b32 s16, s16, 13
	s_add_i32 m0, s16, s36
	s_add_i32 s49, s49, 1
	global_load_lds_dwordx4 v98, s[0:1]
	s_waitcnt lgkmcnt(4)
	s_barrier
	s_add_i32 s3, s14, 1
	s_lshl_b32 s17, s3, 7
	s_sub_i32 s17, 0x2080, s17
	s_sub_i32 s18, s41, 16
	s_cmp_ge_i32 s3, s18
	s_cselect_b32 s18, 1, 0
	s_cmp_le_i32 s3, s41
	s_cselect_b32 s16, 1, 0
	s_and_b32 s16, s16, s18
	v_add_u32_e32 v152, s17, v146
	v_mad_u32_u24 v139, s16, v152, v157
	ds_read2_b32 v[236:237], v139 offset0:27 offset1:26
	ds_read2_b32 v[238:239], v139 offset0:25 offset1:24
	ds_read2_b32 v[240:241], v139 offset0:19 offset1:18
	ds_read2_b32 v[242:243], v139 offset0:17 offset1:16
	ds_read2_b32 v[244:245], v139 offset0:11 offset1:10
	ds_read2_b32 v[246:247], v139 offset0:9 offset1:8
	ds_read2_b32 v[248:249], v139 offset0:3 offset1:2
	ds_read2_b32 v[250:251], v139 offset0:1 offset1:0
	v_exp_f32_e32 v32, v32
	v_exp_f32_e32 v33, v33
	v_exp_f32_e32 v34, v34
	v_exp_f32_e32 v35, v35
	v_exp_f32_e32 v36, v36
	v_exp_f32_e32 v37, v37
	v_exp_f32_e32 v38, v38
	v_exp_f32_e32 v39, v39
	v_exp_f32_e32 v40, v40
	v_exp_f32_e32 v41, v41
	v_exp_f32_e32 v42, v42
	v_exp_f32_e32 v43, v43
	v_exp_f32_e32 v44, v44
	v_exp_f32_e32 v45, v45
	v_exp_f32_e32 v46, v46
	v_exp_f32_e32 v47, v47
	v_add_f32_e32 v64, v32, v33
	v_add_f32_e32 v64, v64, v34
	v_add_f32_e32 v64, v64, v35
	v_add_f32_e32 v64, v64, v36
	v_add_f32_e32 v64, v64, v37
	v_add_f32_e32 v64, v64, v38
	v_add_f32_e32 v64, v64, v39
	v_add_f32_e32 v64, v64, v40
	v_add_f32_e32 v64, v64, v41
	v_add_f32_e32 v64, v64, v42
	v_add_f32_e32 v64, v64, v43
	v_add_f32_e32 v64, v64, v44
	v_add_f32_e32 v64, v64, v45
	v_add_f32_e32 v64, v64, v46
	v_add_f32_e32 v64, v64, v47
	v_add_f32_e32 v138, v138, v64
	v_cvt_pk_bf16_f32 v130, v32, v33
	v_cvt_pk_bf16_f32 v131, v34, v35
	v_cvt_pk_bf16_f32 v132, v36, v37
	v_cvt_pk_bf16_f32 v133, v38, v39
	v_cvt_pk_bf16_f32 v134, v40, v41
	v_cvt_pk_bf16_f32 v135, v42, v43
	v_cvt_pk_bf16_f32 v136, v44, v45
	v_cvt_pk_bf16_f32 v137, v46, v47
	s_add_i32 s15, s15, 1
	s_waitcnt vmcnt(5)
	s_waitcnt lgkmcnt(0)
	s_barrier
	s_add_i32 s14, s14, 1
	s_cmp_le_i32 s14, s39
	s_cbranch_scc1 .Lws_wloop
	v_mfma_f32_32x32x16_bf16 v[202:217], v[82:85], v[130:133], v[202:217]
	v_mfma_f32_32x32x16_bf16 v[218:233], v[86:89], v[130:133], v[218:233]
	v_mfma_f32_32x32x16_bf16 v[202:217], v[90:93], v[134:137], v[202:217]
	v_mfma_f32_32x32x16_bf16 v[218:233], v[94:97], v[134:137], v[218:233]
	v_mov_b32_e32 v130, 0
	v_mov_b32_e32 v131, 0
	v_mov_b32_e32 v132, 0
	v_mov_b32_e32 v133, 0
	v_mov_b32_e32 v134, 0
	v_mov_b32_e32 v135, 0
	v_mov_b32_e32 v136, 0
	v_mov_b32_e32 v137, 0
	v_and_b32_e32 v152, 0xffff0000, v141
	v_mul_f32_e32 v152, 0xbfb8aa3b, v152
	ds_bpermute_b32 v153, v148, v138
	v_exp_f32_e32 v152, v152
	s_waitcnt lgkmcnt(0)
	v_add_f32_e32 v158, v138, v153
	v_add_f32_e32 v152, 1.0, v152
	v_div_scale_f32 v160, s[16:17], v158, v158, 1.0
	v_rcp_f32_e32 v161, v160
	s_nop 0
	v_fma_f32 v174, -v160, v161, 1.0
	v_fmac_f32_e32 v161, v174, v161
	v_div_scale_f32 v174, vcc, 1.0, v158, 1.0
	v_mul_f32_e32 v175, v174, v161
	v_fma_f32 v176, -v160, v175, v174
	v_fmac_f32_e32 v175, v176, v161
	v_fma_f32 v160, -v160, v175, v174
	v_div_fmas_f32 v160, v160, v161, v175
	v_div_fixup_f32 v159, v160, v158, 1.0
	v_div_scale_f32 v160, s[16:17], v152, v152, 1.0
	v_rcp_f32_e32 v161, v160
	s_nop 0
	v_fma_f32 v174, -v160, v161, 1.0
	v_fmac_f32_e32 v161, v174, v161
	v_div_scale_f32 v174, vcc, 1.0, v152, 1.0
	v_mul_f32_e32 v175, v174, v161
	v_fma_f32 v176, -v160, v175, v174
	v_fmac_f32_e32 v175, v176, v161
	v_fma_f32 v160, -v160, v175, v174
	v_div_fmas_f32 v160, v160, v161, v175
	v_div_fixup_f32 v177, v160, v152, 1.0
	v_cmp_lt_f32_e32 vcc, 0, v158
	s_nop 1
	v_cndmask_b32_e32 v158, 0, v159, vcc
	v_mul_f32_e32 v234, v177, v158
	v_mov_b32_e32 v138, 0
	v_mov_b32_e32 v0, 0
	v_mov_b32_e32 v1, 0
	v_mov_b32_e32 v2, 0
	v_mov_b32_e32 v3, 0
	v_mov_b32_e32 v4, 0
	v_mov_b32_e32 v5, 0
	v_mov_b32_e32 v6, 0
	v_mov_b32_e32 v7, 0
	v_mov_b32_e32 v8, 0
	v_mov_b32_e32 v9, 0
	v_mov_b32_e32 v10, 0
	v_mov_b32_e32 v11, 0
	v_mov_b32_e32 v12, 0
	v_mov_b32_e32 v13, 0
	v_mov_b32_e32 v14, 0
	v_mov_b32_e32 v15, 0
	v_mov_b32_e32 v16, 0
	v_mov_b32_e32 v17, 0
	v_mov_b32_e32 v18, 0
	v_mov_b32_e32 v19, 0
	v_mov_b32_e32 v20, 0
	v_mov_b32_e32 v21, 0
	v_mov_b32_e32 v22, 0
	v_mov_b32_e32 v23, 0
	v_mov_b32_e32 v24, 0
	v_mov_b32_e32 v25, 0
	v_mov_b32_e32 v26, 0
	v_mov_b32_e32 v27, 0
	v_mov_b32_e32 v28, 0
	v_mov_b32_e32 v29, 0
	v_mov_b32_e32 v30, 0
	v_mov_b32_e32 v31, 0
	s_ff1_i32_b32 s14, s19
	s_add_i32 s0, s19, -1
	s_and_b32 s19, s19, s0
	v_bfe_u32 v152, v140, s14, 1
	s_lshl_b32 s17, s14, 8
	s_sub_i32 s17, 0, s17
	v_add_u32_e32 v153, s17, v146
	v_mad_u32_u24 v139, v152, v153, v157
	ds_read2_b32 v[236:237], v139 offset0:27 offset1:26
	ds_read2_b32 v[238:239], v139 offset0:25 offset1:24
	ds_read2_b32 v[240:241], v139 offset0:19 offset1:18
	ds_read2_b32 v[242:243], v139 offset0:17 offset1:16
	ds_read2_b32 v[244:245], v139 offset0:11 offset1:10
	ds_read2_b32 v[246:247], v139 offset0:9 offset1:8
	ds_read2_b32 v[248:249], v139 offset0:3 offset1:2
	ds_read2_b32 v[250:251], v139 offset0:1 offset1:0
	s_waitcnt lgkmcnt(0)
.Lws_sloop:
	v_mfma_f32_32x32x16_bf16 v[0:15], v[82:85], v[130:133], v[0:15]
	v_mfma_f32_32x32x16_bf16 v[16:31], v[86:89], v[130:133], v[16:31]
	v_mfma_f32_32x32x16_bf16 v[0:15], v[90:93], v[134:137], v[0:15]
	v_mfma_f32_32x32x16_bf16 v[16:31], v[94:97], v[134:137], v[16:31]
	s_add_i32 s16, s15, 0
	s_and_b32 s16, s16, 7
	s_lshl_b32 s16, s16, 13
	s_add_i32 s16, s16, 0x15000
	v_add_u32_e32 v99, s16, v144
	ds_read_b128 v[82:85], v99 offset:4096
	ds_read_b128 v[86:89], v99 offset:5120
	ds_read_b128 v[90:93], v99 offset:6144
	ds_read_b128 v[94:97], v99 offset:7168
	v_mfma_f32_32x32x16_bf16 v[32:47], v[66:69], v[48:51], v[236:251]
	v_mfma_f32_32x32x16_bf16 v[32:47], v[70:73], v[52:55], v[32:47]
	v_mfma_f32_32x32x16_bf16 v[32:47], v[74:77], v[56:59], v[32:47]
	v_mfma_f32_32x32x16_bf16 v[32:47], v[78:81], v[60:63], v[32:47]
	s_add_i32 s16, s15, 1
	s_and_b32 s16, s16, 7
	s_lshl_b32 s16, s16, 13
	s_add_i32 s16, s16, 0x15000
	v_add_u32_e32 v101, s16, v144
	ds_read_b128 v[66:69], v101
	ds_read_b128 v[70:73], v101 offset:1024
	ds_read_b128 v[74:77], v101 offset:2048
	ds_read_b128 v[78:81], v101 offset:3072
	s_cmp_eq_u32 s46, 0
	s_cbranch_scc0 .Lws_ga8_sel
	s_add_i32 s47, s47, 1
	s_cmp_le_i32 s47, s39
	s_cbranch_scc1 .Lws_ga8_done
	s_mov_b32 s46, 1
	s_branch .Lws_ga8_blk

.Lws_ga8_done:
	s_lshl_b32 s16, s47, 12
	s_cmp_eq_u32 s46, 0
	s_cselect_b32 s0, s42, s44
	s_cselect_b32 s1, s43, s45
	s_add_u32 s0, s0, s16
	s_addc_u32 s1, s1, 0
	s_and_b32 s16, s49, 7
	s_lshl_b32 s16, s16, 13
	s_add_i32 m0, s16, s36
	s_add_i32 s49, s49, 1
	global_load_lds_dwordx4 v98, s[0:1]
	s_waitcnt lgkmcnt(4)
	s_barrier
	v_bfe_u32 v152, v140, s14, 1
	s_lshl_b32 s17, s14, 8
	s_sub_i32 s17, 0xffffff80, s17
	s_lshl_b32 s16, s14, 6
	s_cmp_lt_i32 s16, s35
	s_cselect_b32 s16, 1, 0
	v_and_b32_e32 v152, s16, v152
	v_add_u32_e32 v153, s17, v146
	v_mad_u32_u24 v139, v152, v153, v157
	ds_read2_b32 v[236:237], v139 offset0:27 offset1:26
	ds_read2_b32 v[238:239], v139 offset0:25 offset1:24
	ds_read2_b32 v[240:241], v139 offset0:19 offset1:18
	ds_read2_b32 v[242:243], v139 offset0:17 offset1:16
	ds_read2_b32 v[244:245], v139 offset0:11 offset1:10
	ds_read2_b32 v[246:247], v139 offset0:9 offset1:8
	ds_read2_b32 v[248:249], v139 offset0:3 offset1:2
	ds_read2_b32 v[250:251], v139 offset0:1 offset1:0
	v_exp_f32_e32 v32, v32
	v_exp_f32_e32 v33, v33
	v_exp_f32_e32 v34, v34
	v_exp_f32_e32 v35, v35
	v_exp_f32_e32 v36, v36
	v_exp_f32_e32 v37, v37
	v_exp_f32_e32 v38, v38
	v_exp_f32_e32 v39, v39
	v_exp_f32_e32 v40, v40
	v_exp_f32_e32 v41, v41
	v_exp_f32_e32 v42, v42
	v_exp_f32_e32 v43, v43
	v_exp_f32_e32 v44, v44
	v_exp_f32_e32 v45, v45
	v_exp_f32_e32 v46, v46
	v_exp_f32_e32 v47, v47
	v_add_f32_e32 v64, v32, v33
	v_add_f32_e32 v64, v64, v34
	v_add_f32_e32 v64, v64, v35
	v_add_f32_e32 v64, v64, v36
	v_add_f32_e32 v64, v64, v37
	v_add_f32_e32 v64, v64, v38
	v_add_f32_e32 v64, v64, v39
	v_add_f32_e32 v64, v64, v40
	v_add_f32_e32 v64, v64, v41
	v_add_f32_e32 v64, v64, v42
	v_add_f32_e32 v64, v64, v43
	v_add_f32_e32 v64, v64, v44
	v_add_f32_e32 v64, v64, v45
	v_add_f32_e32 v64, v64, v46
	v_add_f32_e32 v64, v64, v47
	v_add_f32_e32 v138, v138, v64
	v_cvt_pk_bf16_f32 v130, v32, v33
	v_cvt_pk_bf16_f32 v131, v34, v35
	v_cvt_pk_bf16_f32 v132, v36, v37
	v_cvt_pk_bf16_f32 v133, v38, v39
	v_cvt_pk_bf16_f32 v134, v40, v41
	v_cvt_pk_bf16_f32 v135, v42, v43
	v_cvt_pk_bf16_f32 v136, v44, v45
	v_cvt_pk_bf16_f32 v137, v46, v47
	s_add_i32 s15, s15, 1
	s_waitcnt vmcnt(5)
	s_waitcnt lgkmcnt(0)
	s_barrier
	v_mfma_f32_32x32x16_bf16 v[0:15], v[82:85], v[130:133], v[0:15]
	v_mfma_f32_32x32x16_bf16 v[16:31], v[86:89], v[130:133], v[16:31]
	v_mfma_f32_32x32x16_bf16 v[0:15], v[90:93], v[134:137], v[0:15]
	v_mfma_f32_32x32x16_bf16 v[16:31], v[94:97], v[134:137], v[16:31]
	s_add_i32 s16, s15, 0
	s_and_b32 s16, s16, 7
	s_lshl_b32 s16, s16, 13
	s_add_i32 s16, s16, 0x15000
	v_add_u32_e32 v99, s16, v144
	ds_read_b128 v[82:85], v99 offset:4096
	ds_read_b128 v[86:89], v99 offset:5120
	ds_read_b128 v[90:93], v99 offset:6144
	ds_read_b128 v[94:97], v99 offset:7168
	v_mfma_f32_32x32x16_bf16 v[32:47], v[66:69], v[48:51], v[236:251]
	v_mfma_f32_32x32x16_bf16 v[32:47], v[70:73], v[52:55], v[32:47]
	v_mfma_f32_32x32x16_bf16 v[32:47], v[74:77], v[56:59], v[32:47]
	v_mfma_f32_32x32x16_bf16 v[32:47], v[78:81], v[60:63], v[32:47]
	s_add_i32 s16, s15, 1
	s_and_b32 s16, s16, 7
	s_lshl_b32 s16, s16, 13
	s_add_i32 s16, s16, 0x15000
	v_add_u32_e32 v101, s16, v144
	ds_read_b128 v[66:69], v101
	ds_read_b128 v[70:73], v101 offset:1024
	ds_read_b128 v[74:77], v101 offset:2048
	ds_read_b128 v[78:81], v101 offset:3072
	s_cmp_eq_u32 s46, 0
	s_cbranch_scc0 .Lws_ga9_sel
	s_add_i32 s47, s47, 1
	s_cmp_le_i32 s47, s39
	s_cbranch_scc1 .Lws_ga9_done
	s_mov_b32 s46, 1
	s_branch .Lws_ga9_blk

.Lws_ga9_done:
	s_lshl_b32 s16, s47, 12
	s_cmp_eq_u32 s46, 0
	s_cselect_b32 s0, s42, s44
	s_cselect_b32 s1, s43, s45
	s_add_u32 s0, s0, s16
	s_addc_u32 s1, s1, 0
	s_and_b32 s16, s49, 7
	s_lshl_b32 s16, s16, 13
	s_add_i32 m0, s16, s36
	s_add_i32 s49, s49, 1
	global_load_lds_dwordx4 v98, s[0:1]
	s_waitcnt lgkmcnt(4)
	s_barrier
	s_ff1_i32_b32 s3, s19
	s_cmp_eq_u32 s19, 0
	s_cselect_b32 s3, s14, s3
	v_bfe_u32 v152, v140, s3, 1
	s_lshl_b32 s17, s3, 8
	s_sub_i32 s17, 0, s17
	v_add_u32_e32 v153, s17, v146
	v_mad_u32_u24 v139, v152, v153, v157
	ds_read2_b32 v[236:237], v139 offset0:27 offset1:26
	ds_read2_b32 v[238:239], v139 offset0:25 offset1:24
	ds_read2_b32 v[240:241], v139 offset0:19 offset1:18
	ds_read2_b32 v[242:243], v139 offset0:17 offset1:16
	ds_read2_b32 v[244:245], v139 offset0:11 offset1:10
	ds_read2_b32 v[246:247], v139 offset0:9 offset1:8
	ds_read2_b32 v[248:249], v139 offset0:3 offset1:2
	ds_read2_b32 v[250:251], v139 offset0:1 offset1:0
	v_exp_f32_e32 v32, v32
	v_exp_f32_e32 v33, v33
	v_exp_f32_e32 v34, v34
	v_exp_f32_e32 v35, v35
	v_exp_f32_e32 v36, v36
	v_exp_f32_e32 v37, v37
	v_exp_f32_e32 v38, v38
	v_exp_f32_e32 v39, v39
	v_exp_f32_e32 v40, v40
	v_exp_f32_e32 v41, v41
	v_exp_f32_e32 v42, v42
	v_exp_f32_e32 v43, v43
	v_exp_f32_e32 v44, v44
	v_exp_f32_e32 v45, v45
	v_exp_f32_e32 v46, v46
	v_exp_f32_e32 v47, v47
	v_add_f32_e32 v64, v32, v33
	v_add_f32_e32 v64, v64, v34
	v_add_f32_e32 v64, v64, v35
	v_add_f32_e32 v64, v64, v36
	v_add_f32_e32 v64, v64, v37
	v_add_f32_e32 v64, v64, v38
	v_add_f32_e32 v64, v64, v39
	v_add_f32_e32 v64, v64, v40
	v_add_f32_e32 v64, v64, v41
	v_add_f32_e32 v64, v64, v42
	v_add_f32_e32 v64, v64, v43
	v_add_f32_e32 v64, v64, v44
	v_add_f32_e32 v64, v64, v45
	v_add_f32_e32 v64, v64, v46
	v_add_f32_e32 v64, v64, v47
	v_add_f32_e32 v138, v138, v64
	v_cvt_pk_bf16_f32 v130, v32, v33
	v_cvt_pk_bf16_f32 v131, v34, v35
	v_cvt_pk_bf16_f32 v132, v36, v37
	v_cvt_pk_bf16_f32 v133, v38, v39
	v_cvt_pk_bf16_f32 v134, v40, v41
	v_cvt_pk_bf16_f32 v135, v42, v43
	v_cvt_pk_bf16_f32 v136, v44, v45
	v_cvt_pk_bf16_f32 v137, v46, v47
	s_add_i32 s15, s15, 1
	s_waitcnt vmcnt(5)
	s_waitcnt lgkmcnt(0)
	s_barrier
	s_ff1_i32_b32 s3, s19
	s_add_i32 s0, s19, -1
	s_and_b32 s0, s19, s0
	s_cmp_eq_u32 s19, 0
	s_mov_b32 s19, s0
	s_cselect_b32 s14, s14, s3
	s_cbranch_scc0 .Lws_sloop
.Lws_final:
	v_mfma_f32_32x32x16_bf16 v[0:15], v[82:85], v[130:133], v[0:15]
	v_mfma_f32_32x32x16_bf16 v[16:31], v[86:89], v[130:133], v[16:31]
	v_mfma_f32_32x32x16_bf16 v[0:15], v[90:93], v[134:137], v[0:15]
	v_mfma_f32_32x32x16_bf16 v[16:31], v[94:97], v[134:137], v[16:31]
	s_cmp_lg_u32 s21, 0
	s_cbranch_scc1 .Lws_skew1
	s_barrier
.Lws_skew1:
	s_lshl_b32 s0, s40, 8
	s_add_u32 s0, s8, s0
	s_addc_u32 s1, s9, 0
	s_waitcnt lgkmcnt(0)
	global_load_dwordx4 v[98:101], v156, s[0:1] offset:0
	global_load_dwordx4 v[102:105], v156, s[0:1] offset:32
	global_load_dwordx4 v[106:109], v156, s[0:1] offset:64
	global_load_dwordx4 v[110:113], v156, s[0:1] offset:96
	global_load_dwordx4 v[114:117], v156, s[0:1] offset:128
	global_load_dwordx4 v[118:121], v156, s[0:1] offset:160
	global_load_dwordx4 v[122:125], v156, s[0:1] offset:192
	global_load_dwordx4 v[126:129], v156, s[0:1] offset:224
	v_lshlrev_b32_e32 v152, 16, v141
	v_mul_f32_e32 v152, 0xbfb8aa3b, v152
	ds_bpermute_b32 v153, v148, v138
	v_exp_f32_e32 v152, v152
	s_waitcnt lgkmcnt(0)
	v_add_f32_e32 v158, v138, v153
	v_add_f32_e32 v152, 1.0, v152
	v_div_scale_f32 v160, s[16:17], v158, v158, 1.0
	v_rcp_f32_e32 v161, v160
	s_nop 0
	v_fma_f32 v174, -v160, v161, 1.0
	v_fmac_f32_e32 v161, v174, v161
	v_div_scale_f32 v174, vcc, 1.0, v158, 1.0
	v_mul_f32_e32 v175, v174, v161
	v_fma_f32 v176, -v160, v175, v174
	v_fmac_f32_e32 v175, v176, v161
	v_fma_f32 v160, -v160, v175, v174
	v_div_fmas_f32 v160, v160, v161, v175
	v_div_fixup_f32 v159, v160, v158, 1.0
	v_div_scale_f32 v160, s[16:17], v152, v152, 1.0
	v_rcp_f32_e32 v161, v160
	s_nop 0
	v_fma_f32 v174, -v160, v161, 1.0
	v_fmac_f32_e32 v161, v174, v161
	v_div_scale_f32 v174, vcc, 1.0, v152, 1.0
	v_mul_f32_e32 v175, v174, v161
	v_fma_f32 v176, -v160, v175, v174
	v_fmac_f32_e32 v175, v176, v161
	v_fma_f32 v160, -v160, v175, v174
	v_div_fmas_f32 v160, v160, v161, v175
	v_div_fixup_f32 v177, v160, v152, 1.0
	v_cmp_lt_f32_e32 vcc, 0, v158
	s_nop 1
	v_cndmask_b32_e32 v158, 0, v159, vcc
	v_mul_f32_e32 v200, v177, v158
	s_waitcnt vmcnt(7)
	v_pk_fma_f32 v[98:99], v[202:203], v[234:235], v[98:99] op_sel_hi:[1,0,1]
	v_pk_fma_f32 v[100:101], v[204:205], v[234:235], v[100:101] op_sel_hi:[1,0,1]
	v_pk_fma_f32 v[98:99], v[0:1], v[200:201], v[98:99] op_sel_hi:[1,0,1]
	v_pk_fma_f32 v[100:101], v[2:3], v[200:201], v[100:101] op_sel_hi:[1,0,1]
	s_waitcnt vmcnt(6)
	v_pk_fma_f32 v[102:103], v[206:207], v[234:235], v[102:103] op_sel_hi:[1,0,1]
	v_pk_fma_f32 v[104:105], v[208:209], v[234:235], v[104:105] op_sel_hi:[1,0,1]
	v_pk_fma_f32 v[102:103], v[4:5], v[200:201], v[102:103] op_sel_hi:[1,0,1]
	v_pk_fma_f32 v[104:105], v[6:7], v[200:201], v[104:105] op_sel_hi:[1,0,1]
	s_waitcnt vmcnt(5)
	v_pk_fma_f32 v[106:107], v[210:211], v[234:235], v[106:107] op_sel_hi:[1,0,1]
	v_pk_fma_f32 v[108:109], v[212:213], v[234:235], v[108:109] op_sel_hi:[1,0,1]
	v_pk_fma_f32 v[106:107], v[8:9], v[200:201], v[106:107] op_sel_hi:[1,0,1]
	v_pk_fma_f32 v[108:109], v[10:11], v[200:201], v[108:109] op_sel_hi:[1,0,1]
	s_waitcnt vmcnt(4)
	v_pk_fma_f32 v[110:111], v[214:215], v[234:235], v[110:111] op_sel_hi:[1,0,1]
	v_pk_fma_f32 v[112:113], v[216:217], v[234:235], v[112:113] op_sel_hi:[1,0,1]
	v_pk_fma_f32 v[110:111], v[12:13], v[200:201], v[110:111] op_sel_hi:[1,0,1]
	v_pk_fma_f32 v[112:113], v[14:15], v[200:201], v[112:113] op_sel_hi:[1,0,1]
	s_waitcnt vmcnt(3)
	v_pk_fma_f32 v[114:115], v[218:219], v[234:235], v[114:115] op_sel_hi:[1,0,1]
	v_pk_fma_f32 v[116:117], v[220:221], v[234:235], v[116:117] op_sel_hi:[1,0,1]
	v_pk_fma_f32 v[114:115], v[16:17], v[200:201], v[114:115] op_sel_hi:[1,0,1]
	v_pk_fma_f32 v[116:117], v[18:19], v[200:201], v[116:117] op_sel_hi:[1,0,1]
	s_waitcnt vmcnt(2)
	v_pk_fma_f32 v[118:119], v[222:223], v[234:235], v[118:119] op_sel_hi:[1,0,1]
	v_pk_fma_f32 v[120:121], v[224:225], v[234:235], v[120:121] op_sel_hi:[1,0,1]
	v_pk_fma_f32 v[118:119], v[20:21], v[200:201], v[118:119] op_sel_hi:[1,0,1]
	v_pk_fma_f32 v[120:121], v[22:23], v[200:201], v[120:121] op_sel_hi:[1,0,1]
	s_waitcnt vmcnt(1)
	v_pk_fma_f32 v[122:123], v[226:227], v[234:235], v[122:123] op_sel_hi:[1,0,1]
	v_pk_fma_f32 v[124:125], v[228:229], v[234:235], v[124:125] op_sel_hi:[1,0,1]
	v_pk_fma_f32 v[122:123], v[24:25], v[200:201], v[122:123] op_sel_hi:[1,0,1]
	v_pk_fma_f32 v[124:125], v[26:27], v[200:201], v[124:125] op_sel_hi:[1,0,1]
	s_waitcnt vmcnt(0)
	v_pk_fma_f32 v[126:127], v[230:231], v[234:235], v[126:127] op_sel_hi:[1,0,1]
	v_pk_fma_f32 v[128:129], v[232:233], v[234:235], v[128:129] op_sel_hi:[1,0,1]
	v_pk_fma_f32 v[126:127], v[28:29], v[200:201], v[126:127] op_sel_hi:[1,0,1]
	v_pk_fma_f32 v[128:129], v[30:31], v[200:201], v[128:129] op_sel_hi:[1,0,1]
	global_store_dwordx4 v156, v[98:101], s[0:1] offset:0
	global_store_dwordx4 v156, v[102:105], s[0:1] offset:32
	global_store_dwordx4 v156, v[106:109], s[0:1] offset:64
	global_store_dwordx4 v156, v[110:113], s[0:1] offset:96
	global_store_dwordx4 v156, v[114:117], s[0:1] offset:128
	global_store_dwordx4 v156, v[118:121], s[0:1] offset:160
	global_store_dwordx4 v156, v[122:125], s[0:1] offset:192
	global_store_dwordx4 v156, v[126:129], s[0:1] offset:224
	v_readlane_b32 s35, v255, 1
	s_mov_b64 s[0:1], 0
	s_barrier
	s_branch .LBB0_210

.LBB0_358:
	s_or_b64 exec, exec, s[0:1]
	s_lshr_b32 s3, s2, 6
	s_and_b32 s0, s2, 63
	s_sub_i32 s12, 63, s0
	v_readlane_b32 s0, v253, 31
	v_and_b32_e32 v152, 31, v186
	v_bfe_u32 v153, v186, 5, 1
	s_lshl_b32 s1, s0, 2
	s_add_i32 s1, s1, s3
	s_lshl_b32 s1, s1, 18
	s_add_u32 s40, s16, s1
	s_addc_u32 s41, s17, 0
	s_add_u32 s42, s14, s1
	s_addc_u32 s43, s15, 0
	s_lshl_b32 s1, s0, 10
	s_lshl_b32 s4, s12, 5
	s_add_i32 s1, s1, s4
	v_add_u32_e32 v154, s1, v152
	v_lshlrev_b32_e32 v155, 10, v154
	v_lshl_add_u32 v155, v153, 4, v155
	s_lshl_b32 s1, s3, 7
	s_add_u32 s4, s10, s1
	s_addc_u32 s5, s11, 0
	global_load_dwordx4 v[48:51], v155, s[4:5]
	global_load_dwordx4 v[52:55], v155, s[4:5] offset:32
	global_load_dwordx4 v[56:59], v155, s[4:5] offset:64
	global_load_dwordx4 v[60:63], v155, s[4:5] offset:96
	v_and_b32_e32 v200, 63, v186
	v_lshlrev_b32_e32 v200, 4, v200
	v_lshlrev_b32_e32 v201, 5, v152
	v_lshl_add_u32 v201, v153, 4, v201
	s_lshl_b32 s1, s12, 12
	s_add_u32 s4, s40, s1
	s_addc_u32 s5, s41, 0
	global_load_dwordx4 v[66:69], v200, s[4:5]
	global_load_dwordx4 v[70:73], v200, s[4:5] offset:1024
	global_load_dwordx4 v[74:77], v200, s[4:5] offset:2048
	global_load_dwordx4 v[78:81], v200, s[4:5] offset:3072
	v_xor_b32_e32 v114, 32, v190
	v_lshlrev_b32_e32 v114, 2, v114
	v_lshlrev_b32_e32 v115, 2, v153
	v_sub_u32_e32 v115, v152, v115
	v_sub_u32_e32 v116, 1, v153
	v_sub_u32_e32 v116, 0, v116
	v_lshlrev_b32_e32 v156, 13, v154
	v_lshl_add_u32 v156, v153, 4, v156
	s_lshl_b32 s1, s3, 8
	s_add_i32 s1, s1, 0x1800
	v_add_u32_e32 v156, s1, v156
	s_add_u32 s4, s54, 0x20000000
	s_addc_u32 s5, s55, 0
	v_mov_b32_e32 v161, s5
	v_add_co_u32_e32 v160, vcc, s4, v156
	s_nop 1
	v_addc_co_u32_e32 v161, vcc, 0, v161, vcc
	v_mov_b32_e32 v127, 0
	v_mov_b32_e32 v0, 0
	v_mov_b32_e32 v1, 0
	v_mov_b32_e32 v2, 0
	v_mov_b32_e32 v3, 0
	v_mov_b32_e32 v4, 0
	v_mov_b32_e32 v5, 0
	v_mov_b32_e32 v6, 0
	v_mov_b32_e32 v7, 0
	v_mov_b32_e32 v8, 0
	v_mov_b32_e32 v9, 0
	v_mov_b32_e32 v10, 0
	v_mov_b32_e32 v11, 0
	v_mov_b32_e32 v12, 0
	v_mov_b32_e32 v13, 0
	v_mov_b32_e32 v14, 0
	v_mov_b32_e32 v15, 0
	v_mov_b32_e32 v16, 0
	v_mov_b32_e32 v17, 0
	v_mov_b32_e32 v18, 0
	v_mov_b32_e32 v19, 0
	v_mov_b32_e32 v20, 0
	v_mov_b32_e32 v21, 0
	v_mov_b32_e32 v22, 0
	v_mov_b32_e32 v23, 0
	v_mov_b32_e32 v24, 0
	v_mov_b32_e32 v25, 0
	v_mov_b32_e32 v26, 0
	v_mov_b32_e32 v27, 0
	v_mov_b32_e32 v28, 0
	v_mov_b32_e32 v29, 0
	v_mov_b32_e32 v30, 0
	v_mov_b32_e32 v31, 0
	s_sub_i32 s0, s12, 1
	s_max_i32 s0, s0, 0
	s_lshl_b32 s0, s0, 12
	s_add_u32 s2, s40, s0
	s_addc_u32 s3, s41, 0
	s_lshl_b32 s0, s12, 12
	s_add_u32 s4, s42, s0
	s_addc_u32 s5, s43, 0
	s_waitcnt vmcnt(0)
	global_load_dwordx4 v[82:85], v200, s[2:3]
	global_load_dwordx4 v[86:89], v200, s[2:3] offset:1024
	global_load_dwordx4 v[90:93], v200, s[2:3] offset:2048
	global_load_dwordx4 v[94:97], v200, s[2:3] offset:3072
	global_load_dwordx4 v[98:101], v201, s[4:5]
	global_load_dwordx4 v[102:105], v201, s[4:5] offset:1024
	global_load_dwordx4 v[106:109], v201, s[4:5] offset:2048
	global_load_dwordx4 v[110:113], v201, s[4:5] offset:3072
	v_mfma_f32_32x32x16_bf16 v[32:47], v[66:69], v[48:51], 0
	v_mfma_f32_32x32x16_bf16 v[32:47], v[70:73], v[52:55], v[32:47]
	v_mfma_f32_32x32x16_bf16 v[32:47], v[74:77], v[56:59], v[32:47]
	v_mfma_f32_32x32x16_bf16 v[32:47], v[78:81], v[60:63], v[32:47]
	s_nop 11
	v_mul_f32_e64 v152, |v44|, s67
	v_mul_f32_e64 v153, |v45|, s67
	v_mul_f32_e64 v154, |v46|, s67
	v_mul_f32_e64 v155, |v47|, s67
	v_exp_f32_e32 v152, v152
	v_exp_f32_e32 v153, v153
	v_exp_f32_e32 v154, v154
	v_exp_f32_e32 v155, v155
	v_max_f32_e32 v140, 0, v44
	v_max_f32_e32 v141, 0, v45
	v_max_f32_e32 v142, 0, v46
	v_max_f32_e32 v143, 0, v47
	v_add_f32_e32 v152, 1.0, v152
	v_add_f32_e32 v153, 1.0, v153
	v_add_f32_e32 v154, 1.0, v154
	v_add_f32_e32 v155, 1.0, v155
	v_log_f32_e32 v152, v152
	v_log_f32_e32 v153, v153
	v_log_f32_e32 v154, v154
	v_log_f32_e32 v155, v155
	s_nop 0
	v_mul_f32_e32 v156, 0x3f317217, v152
	v_mul_f32_e32 v157, 0x3f317217, v153
	v_mul_f32_e32 v158, 0x3f317217, v154
	v_mul_f32_e32 v159, 0x3f317217, v155
	v_fma_f32 v156, v152, s78, -v156
	v_fma_f32 v157, v153, s78, -v157
	v_fma_f32 v158, v154, s78, -v158
	v_fma_f32 v159, v155, s78, -v159
	v_fmac_f32_e32 v156, 0x3377d1cf, v152
	v_fmac_f32_e32 v157, 0x3377d1cf, v153
	v_fmac_f32_e32 v158, 0x3377d1cf, v154
	v_fmac_f32_e32 v159, 0x3377d1cf, v155
	v_fmac_f32_e32 v156, 0x3f317217, v152
	v_fmac_f32_e32 v157, 0x3f317217, v153
	v_fmac_f32_e32 v158, 0x3f317217, v154
	v_fmac_f32_e32 v159, 0x3f317217, v155
	v_add_f32_e32 v140, v140, v156
	v_add_f32_e32 v141, v141, v157
	v_add_f32_e32 v142, v142, v158
	v_add_f32_e32 v143, v143, v159
	v_sub_f32_e32 v44, v44, v140
	v_sub_f32_e32 v45, v45, v141
	v_sub_f32_e32 v46, v46, v142
	v_sub_f32_e32 v47, v47, v143
	v_cmp_lt_i32_e64 s[0:1], 24, v115
	v_cmp_lt_i32_e64 s[2:3], 25, v115
	v_cmp_lt_i32_e64 s[4:5], 26, v115
	v_cmp_lt_i32_e64 s[6:7], 27, v115
	s_nop 1
	v_cndmask_b32_e64 v140, 0, v140, s[0:1]
	v_cndmask_b32_e64 v44, v191, v44, s[0:1]
	v_cndmask_b32_e64 v141, 0, v141, s[2:3]
	v_cndmask_b32_e64 v45, v191, v45, s[2:3]
	v_cndmask_b32_e64 v142, 0, v142, s[4:5]
	v_cndmask_b32_e64 v46, v191, v46, s[4:5]
	v_cndmask_b32_e64 v143, 0, v143, s[6:7]
	v_cndmask_b32_e64 v47, v191, v47, s[6:7]
	v_add_f32_e32 v152, v140, v141
	v_add_f32_e32 v153, v142, v143
	v_add_f32_e32 v122, v152, v153
	ds_bpermute_b32 v126, v114, v122
	v_mul_f32_e64 v152, |v40|, s67
	v_mul_f32_e64 v153, |v41|, s67
	v_mul_f32_e64 v154, |v42|, s67
	v_mul_f32_e64 v155, |v43|, s67
	v_exp_f32_e32 v152, v152
	v_exp_f32_e32 v153, v153
	v_exp_f32_e32 v154, v154
	v_exp_f32_e32 v155, v155
	v_max_f32_e32 v136, 0, v40
	v_max_f32_e32 v137, 0, v41
	v_max_f32_e32 v138, 0, v42
	v_max_f32_e32 v139, 0, v43
	v_add_f32_e32 v152, 1.0, v152
	v_add_f32_e32 v153, 1.0, v153
	v_add_f32_e32 v154, 1.0, v154
	v_add_f32_e32 v155, 1.0, v155
	v_log_f32_e32 v152, v152
	v_log_f32_e32 v153, v153
	v_log_f32_e32 v154, v154
	v_log_f32_e32 v155, v155
	s_nop 0
	v_mul_f32_e32 v156, 0x3f317217, v152
	v_mul_f32_e32 v157, 0x3f317217, v153
	v_mul_f32_e32 v158, 0x3f317217, v154
	v_mul_f32_e32 v159, 0x3f317217, v155
	v_fma_f32 v156, v152, s78, -v156
	v_fma_f32 v157, v153, s78, -v157
	v_fma_f32 v158, v154, s78, -v158
	v_fma_f32 v159, v155, s78, -v159
	v_fmac_f32_e32 v156, 0x3377d1cf, v152
	v_fmac_f32_e32 v157, 0x3377d1cf, v153
	v_fmac_f32_e32 v158, 0x3377d1cf, v154
	v_fmac_f32_e32 v159, 0x3377d1cf, v155
	v_fmac_f32_e32 v156, 0x3f317217, v152
	v_fmac_f32_e32 v157, 0x3f317217, v153
	v_fmac_f32_e32 v158, 0x3f317217, v154
	v_fmac_f32_e32 v159, 0x3f317217, v155
	v_add_f32_e32 v136, v136, v156
	v_add_f32_e32 v137, v137, v157
	v_add_f32_e32 v138, v138, v158
	v_add_f32_e32 v139, v139, v159
	v_sub_f32_e32 v40, v40, v136
	v_sub_f32_e32 v41, v41, v137
	v_sub_f32_e32 v42, v42, v138
	v_sub_f32_e32 v43, v43, v139
	v_cmp_lt_i32_e64 s[0:1], 16, v115
	v_cmp_lt_i32_e64 s[2:3], 17, v115
	v_cmp_lt_i32_e64 s[4:5], 18, v115
	v_cmp_lt_i32_e64 s[6:7], 19, v115
	s_nop 1
	v_cndmask_b32_e64 v136, 0, v136, s[0:1]
	v_cndmask_b32_e64 v40, v191, v40, s[0:1]
	v_cndmask_b32_e64 v137, 0, v137, s[2:3]
	v_cndmask_b32_e64 v41, v191, v41, s[2:3]
	v_cndmask_b32_e64 v138, 0, v138, s[4:5]
	v_cndmask_b32_e64 v42, v191, v42, s[4:5]
	v_cndmask_b32_e64 v139, 0, v139, s[6:7]
	v_cndmask_b32_e64 v43, v191, v43, s[6:7]
	v_add_f32_e32 v152, v136, v137
	v_add_f32_e32 v153, v138, v139
	v_add_f32_e32 v121, v152, v153
	ds_bpermute_b32 v125, v114, v121
	v_mul_f32_e64 v152, |v36|, s67
	v_mul_f32_e64 v153, |v37|, s67
	v_mul_f32_e64 v154, |v38|, s67
	v_mul_f32_e64 v155, |v39|, s67
	v_exp_f32_e32 v152, v152
	v_exp_f32_e32 v153, v153
	v_exp_f32_e32 v154, v154
	v_exp_f32_e32 v155, v155
	v_max_f32_e32 v132, 0, v36
	v_max_f32_e32 v133, 0, v37
	v_max_f32_e32 v134, 0, v38
	v_max_f32_e32 v135, 0, v39
	v_add_f32_e32 v152, 1.0, v152
	v_add_f32_e32 v153, 1.0, v153
	v_add_f32_e32 v154, 1.0, v154
	v_add_f32_e32 v155, 1.0, v155
	v_log_f32_e32 v152, v152
	v_log_f32_e32 v153, v153
	v_log_f32_e32 v154, v154
	v_log_f32_e32 v155, v155
	s_nop 0
	v_mul_f32_e32 v156, 0x3f317217, v152
	v_mul_f32_e32 v157, 0x3f317217, v153
	v_mul_f32_e32 v158, 0x3f317217, v154
	v_mul_f32_e32 v159, 0x3f317217, v155
	v_fma_f32 v156, v152, s78, -v156
	v_fma_f32 v157, v153, s78, -v157
	v_fma_f32 v158, v154, s78, -v158
	v_fma_f32 v159, v155, s78, -v159
	v_fmac_f32_e32 v156, 0x3377d1cf, v152
	v_fmac_f32_e32 v157, 0x3377d1cf, v153
	v_fmac_f32_e32 v158, 0x3377d1cf, v154
	v_fmac_f32_e32 v159, 0x3377d1cf, v155
	v_fmac_f32_e32 v156, 0x3f317217, v152
	v_fmac_f32_e32 v157, 0x3f317217, v153
	v_fmac_f32_e32 v158, 0x3f317217, v154
	v_fmac_f32_e32 v159, 0x3f317217, v155
	v_add_f32_e32 v132, v132, v156
	v_add_f32_e32 v133, v133, v157
	v_add_f32_e32 v134, v134, v158
	v_add_f32_e32 v135, v135, v159
	v_sub_f32_e32 v36, v36, v132
	v_sub_f32_e32 v37, v37, v133
	v_sub_f32_e32 v38, v38, v134
	v_sub_f32_e32 v39, v39, v135
	v_cmp_lt_i32_e64 s[0:1], 8, v115
	v_cmp_lt_i32_e64 s[2:3], 9, v115
	v_cmp_lt_i32_e64 s[4:5], 10, v115
	v_cmp_lt_i32_e64 s[6:7], 11, v115
	s_nop 1
	v_cndmask_b32_e64 v132, 0, v132, s[0:1]
	v_cndmask_b32_e64 v36, v191, v36, s[0:1]
	v_cndmask_b32_e64 v133, 0, v133, s[2:3]
	v_cndmask_b32_e64 v37, v191, v37, s[2:3]
	v_cndmask_b32_e64 v134, 0, v134, s[4:5]
	v_cndmask_b32_e64 v38, v191, v38, s[4:5]
	v_cndmask_b32_e64 v135, 0, v135, s[6:7]
	v_cndmask_b32_e64 v39, v191, v39, s[6:7]
	v_add_f32_e32 v152, v132, v133
	v_add_f32_e32 v153, v134, v135
	v_add_f32_e32 v120, v152, v153
	ds_bpermute_b32 v124, v114, v120
	v_mul_f32_e64 v152, |v32|, s67
	v_mul_f32_e64 v153, |v33|, s67
	v_mul_f32_e64 v154, |v34|, s67
	v_mul_f32_e64 v155, |v35|, s67
	v_exp_f32_e32 v152, v152
	v_exp_f32_e32 v153, v153
	v_exp_f32_e32 v154, v154
	v_exp_f32_e32 v155, v155
	v_max_f32_e32 v128, 0, v32
	v_max_f32_e32 v129, 0, v33
	v_max_f32_e32 v130, 0, v34
	v_max_f32_e32 v131, 0, v35
	v_add_f32_e32 v152, 1.0, v152
	v_add_f32_e32 v153, 1.0, v153
	v_add_f32_e32 v154, 1.0, v154
	v_add_f32_e32 v155, 1.0, v155
	v_log_f32_e32 v152, v152
	v_log_f32_e32 v153, v153
	v_log_f32_e32 v154, v154
	v_log_f32_e32 v155, v155
	s_nop 0
	v_mul_f32_e32 v156, 0x3f317217, v152
	v_mul_f32_e32 v157, 0x3f317217, v153
	v_mul_f32_e32 v158, 0x3f317217, v154
	v_mul_f32_e32 v159, 0x3f317217, v155
	v_fma_f32 v156, v152, s78, -v156
	v_fma_f32 v157, v153, s78, -v157
	v_fma_f32 v158, v154, s78, -v158
	v_fma_f32 v159, v155, s78, -v159
	v_fmac_f32_e32 v156, 0x3377d1cf, v152
	v_fmac_f32_e32 v157, 0x3377d1cf, v153
	v_fmac_f32_e32 v158, 0x3377d1cf, v154
	v_fmac_f32_e32 v159, 0x3377d1cf, v155
	v_fmac_f32_e32 v156, 0x3f317217, v152
	v_fmac_f32_e32 v157, 0x3f317217, v153
	v_fmac_f32_e32 v158, 0x3f317217, v154
	v_fmac_f32_e32 v159, 0x3f317217, v155
	v_add_f32_e32 v128, v128, v156
	v_add_f32_e32 v129, v129, v157
	v_add_f32_e32 v130, v130, v158
	v_add_f32_e32 v131, v131, v159
	v_sub_f32_e32 v32, v32, v128
	v_sub_f32_e32 v33, v33, v129
	v_sub_f32_e32 v34, v34, v130
	v_sub_f32_e32 v35, v35, v131
	v_cmp_lt_i32_e64 s[0:1], 0, v115
	v_cmp_lt_i32_e64 s[2:3], 1, v115
	v_cmp_lt_i32_e64 s[4:5], 2, v115
	v_cmp_lt_i32_e64 s[6:7], 3, v115
	s_nop 1
	v_cndmask_b32_e64 v128, 0, v128, s[0:1]
	v_cndmask_b32_e64 v32, v191, v32, s[0:1]
	v_cndmask_b32_e64 v129, 0, v129, s[2:3]
	v_cndmask_b32_e64 v33, v191, v33, s[2:3]
	v_cndmask_b32_e64 v130, 0, v130, s[4:5]
	v_cndmask_b32_e64 v34, v191, v34, s[4:5]
	v_cndmask_b32_e64 v131, 0, v131, s[6:7]
	v_cndmask_b32_e64 v35, v191, v35, s[6:7]
	v_add_f32_e32 v152, v128, v129
	v_add_f32_e32 v153, v130, v131
	v_add_f32_e32 v119, v152, v153
	ds_bpermute_b32 v123, v114, v119
	s_waitcnt lgkmcnt(3)
	v_and_b32_e32 v152, v116, v126
	v_add_f32_e32 v153, v122, v126
	v_sub_f32_e32 v199, v127, v152
	v_sub_f32_e32 v127, v127, v153
	v_mov_b32_e32 v159, v199
	v_sub_f32_e32 v158, v159, v143
	v_sub_f32_e32 v157, v158, v142
	v_sub_f32_e32 v156, v157, v141
	v_cmp_lt_f32_e64 s[0:1], s81, v44
	v_cmp_lt_f32_e64 s[2:3], s81, v45
	v_cmp_lt_f32_e64 s[4:5], s81, v46
	v_cmp_lt_f32_e64 s[6:7], s81, v47
	v_add_f32_e32 v44, v44, v156
	v_add_f32_e32 v45, v45, v157
	v_add_f32_e32 v46, v46, v158
	v_add_f32_e32 v47, v47, v159
	v_mul_f32_e32 v44, 0x3fb8aa3b, v44
	v_mul_f32_e32 v45, 0x3fb8aa3b, v45
	v_mul_f32_e32 v46, 0x3fb8aa3b, v46
	v_mul_f32_e32 v47, 0x3fb8aa3b, v47
	v_exp_f32_e32 v44, v44
	v_exp_f32_e32 v45, v45
	v_exp_f32_e32 v46, v46
	v_exp_f32_e32 v47, v47
	s_nop 0
	v_cndmask_b32_e64 v44, 0, v44, s[0:1]
	v_cndmask_b32_e64 v45, 0, v45, s[2:3]
	v_cndmask_b32_e64 v46, 0, v46, s[4:5]
	v_cndmask_b32_e64 v47, 0, v47, s[6:7]
	s_waitcnt lgkmcnt(2)
	v_and_b32_e32 v152, v116, v125
	v_add_f32_e32 v153, v121, v125
	v_sub_f32_e32 v199, v127, v152
	v_sub_f32_e32 v127, v127, v153
	v_mov_b32_e32 v159, v199
	v_sub_f32_e32 v158, v159, v139
	v_sub_f32_e32 v157, v158, v138
	v_sub_f32_e32 v156, v157, v137
	v_cmp_lt_f32_e64 s[0:1], s81, v40
	v_cmp_lt_f32_e64 s[2:3], s81, v41
	v_cmp_lt_f32_e64 s[4:5], s81, v42
	v_cmp_lt_f32_e64 s[6:7], s81, v43
	v_add_f32_e32 v40, v40, v156
	v_add_f32_e32 v41, v41, v157
	v_add_f32_e32 v42, v42, v158
	v_add_f32_e32 v43, v43, v159
	v_mul_f32_e32 v40, 0x3fb8aa3b, v40
	v_mul_f32_e32 v41, 0x3fb8aa3b, v41
	v_mul_f32_e32 v42, 0x3fb8aa3b, v42
	v_mul_f32_e32 v43, 0x3fb8aa3b, v43
	v_exp_f32_e32 v40, v40
	v_exp_f32_e32 v41, v41
	v_exp_f32_e32 v42, v42
	v_exp_f32_e32 v43, v43
	s_nop 0
	v_cndmask_b32_e64 v40, 0, v40, s[0:1]
	v_cndmask_b32_e64 v41, 0, v41, s[2:3]
	v_cndmask_b32_e64 v42, 0, v42, s[4:5]
	v_cndmask_b32_e64 v43, 0, v43, s[6:7]
	s_waitcnt lgkmcnt(1)
	v_and_b32_e32 v152, v116, v124
	v_add_f32_e32 v153, v120, v124
	v_sub_f32_e32 v199, v127, v152
	v_sub_f32_e32 v127, v127, v153
	v_mov_b32_e32 v159, v199
	v_sub_f32_e32 v158, v159, v135
	v_sub_f32_e32 v157, v158, v134
	v_sub_f32_e32 v156, v157, v133
	v_cmp_lt_f32_e64 s[0:1], s81, v36
	v_cmp_lt_f32_e64 s[2:3], s81, v37
	v_cmp_lt_f32_e64 s[4:5], s81, v38
	v_cmp_lt_f32_e64 s[6:7], s81, v39
	v_add_f32_e32 v36, v36, v156
	v_add_f32_e32 v37, v37, v157
	v_add_f32_e32 v38, v38, v158
	v_add_f32_e32 v39, v39, v159
	v_mul_f32_e32 v36, 0x3fb8aa3b, v36
	v_mul_f32_e32 v37, 0x3fb8aa3b, v37
	v_mul_f32_e32 v38, 0x3fb8aa3b, v38
	v_mul_f32_e32 v39, 0x3fb8aa3b, v39
	v_exp_f32_e32 v36, v36
	v_exp_f32_e32 v37, v37
	v_exp_f32_e32 v38, v38
	v_exp_f32_e32 v39, v39
	s_nop 0
	v_cndmask_b32_e64 v36, 0, v36, s[0:1]
	v_cndmask_b32_e64 v37, 0, v37, s[2:3]
	v_cndmask_b32_e64 v38, 0, v38, s[4:5]
	v_cndmask_b32_e64 v39, 0, v39, s[6:7]
	s_waitcnt lgkmcnt(0)
	v_and_b32_e32 v152, v116, v123
	v_add_f32_e32 v153, v119, v123
	v_sub_f32_e32 v199, v127, v152
	v_sub_f32_e32 v127, v127, v153
	v_mov_b32_e32 v159, v199
	v_sub_f32_e32 v158, v159, v131
	v_sub_f32_e32 v157, v158, v130
	v_sub_f32_e32 v156, v157, v129
	v_cmp_lt_f32_e64 s[0:1], s81, v32
	v_cmp_lt_f32_e64 s[2:3], s81, v33
	v_cmp_lt_f32_e64 s[4:5], s81, v34
	v_cmp_lt_f32_e64 s[6:7], s81, v35
	v_add_f32_e32 v32, v32, v156
	v_add_f32_e32 v33, v33, v157
	v_add_f32_e32 v34, v34, v158
	v_add_f32_e32 v35, v35, v159
	v_mul_f32_e32 v32, 0x3fb8aa3b, v32
	v_mul_f32_e32 v33, 0x3fb8aa3b, v33
	v_mul_f32_e32 v34, 0x3fb8aa3b, v34
	v_mul_f32_e32 v35, 0x3fb8aa3b, v35
	v_exp_f32_e32 v32, v32
	v_exp_f32_e32 v33, v33
	v_exp_f32_e32 v34, v34
	v_exp_f32_e32 v35, v35
	s_nop 0
	v_cndmask_b32_e64 v32, 0, v32, s[0:1]
	v_cndmask_b32_e64 v33, 0, v33, s[2:3]
	v_cndmask_b32_e64 v34, 0, v34, s[4:5]
	v_cndmask_b32_e64 v35, 0, v35, s[6:7]
	v_cvt_pk_bf16_f32 v144, v32, v33
	v_cvt_pk_bf16_f32 v145, v34, v35
	v_cvt_pk_bf16_f32 v146, v36, v37
	v_cvt_pk_bf16_f32 v147, v38, v39
	v_cvt_pk_bf16_f32 v148, v40, v41
	v_cvt_pk_bf16_f32 v149, v42, v43
	v_cvt_pk_bf16_f32 v150, v44, v45
	v_cvt_pk_bf16_f32 v151, v46, v47
	v_cmp_gt_f32_e32 vcc, s82, v127
	s_waitcnt vmcnt(0)
	v_mfma_f32_32x32x16_bf16 v[16:31], v[98:101], v[144:147], v[16:31]
	v_mfma_f32_32x32x16_bf16 v[0:15], v[102:105], v[144:147], v[0:15]
	v_mfma_f32_32x32x16_bf16 v[16:31], v[106:109], v[148:151], v[16:31]
	v_mfma_f32_32x32x16_bf16 v[0:15], v[110:113], v[148:151], v[0:15]
	v_mov_b64_e32 v[66:67], v[82:83]
	v_mov_b64_e32 v[68:69], v[84:85]
	v_mov_b64_e32 v[70:71], v[86:87]
	v_mov_b64_e32 v[72:73], v[88:89]
	v_mov_b64_e32 v[74:75], v[90:91]
	v_mov_b64_e32 v[76:77], v[92:93]
	v_mov_b64_e32 v[78:79], v[94:95]
	v_mov_b64_e32 v[80:81], v[96:97]
	s_cmp_eq_u64 vcc, exec
	s_cselect_b32 s0, 1, 0
	s_cmp_eq_u32 s12, 0
	s_cselect_b32 s1, 1, 0
	s_or_b32 s0, s0, s1
	s_sub_i32 s12, s12, 1
	s_cmp_lg_u32 s0, 0
	s_cbranch_scc1 .Lsb_done
.Lsb_loop:
	s_sub_i32 s0, s12, 1
	s_max_i32 s0, s0, 0
	s_lshl_b32 s0, s0, 12
	s_add_u32 s2, s40, s0
	s_addc_u32 s3, s41, 0
	s_lshl_b32 s0, s12, 12
	s_add_u32 s4, s42, s0
	s_addc_u32 s5, s43, 0
	s_waitcnt vmcnt(0)
	global_load_dwordx4 v[82:85], v200, s[2:3]
	global_load_dwordx4 v[86:89], v200, s[2:3] offset:1024
	global_load_dwordx4 v[90:93], v200, s[2:3] offset:2048
	global_load_dwordx4 v[94:97], v200, s[2:3] offset:3072
	global_load_dwordx4 v[98:101], v201, s[4:5]
	global_load_dwordx4 v[102:105], v201, s[4:5] offset:1024
	global_load_dwordx4 v[106:109], v201, s[4:5] offset:2048
	global_load_dwordx4 v[110:113], v201, s[4:5] offset:3072
	v_mfma_f32_32x32x16_bf16 v[32:47], v[66:69], v[48:51], 0
	v_mfma_f32_32x32x16_bf16 v[32:47], v[70:73], v[52:55], v[32:47]
	v_mfma_f32_32x32x16_bf16 v[32:47], v[74:77], v[56:59], v[32:47]
	v_mfma_f32_32x32x16_bf16 v[32:47], v[78:81], v[60:63], v[32:47]
	s_nop 11
	v_mul_f32_e64 v152, |v44|, s67
	v_mul_f32_e64 v153, |v45|, s67
	v_mul_f32_e64 v154, |v46|, s67
	v_mul_f32_e64 v155, |v47|, s67
	v_exp_f32_e32 v152, v152
	v_exp_f32_e32 v153, v153
	v_exp_f32_e32 v154, v154
	v_exp_f32_e32 v155, v155
	v_max_f32_e32 v140, 0, v44
	v_max_f32_e32 v141, 0, v45
	v_max_f32_e32 v142, 0, v46
	v_max_f32_e32 v143, 0, v47
	v_add_f32_e32 v152, 1.0, v152
	v_add_f32_e32 v153, 1.0, v153
	v_add_f32_e32 v154, 1.0, v154
	v_add_f32_e32 v155, 1.0, v155
	v_log_f32_e32 v152, v152
	v_log_f32_e32 v153, v153
	v_log_f32_e32 v154, v154
	v_log_f32_e32 v155, v155
	s_nop 0
	v_mul_f32_e32 v156, 0x3f317217, v152
	v_mul_f32_e32 v157, 0x3f317217, v153
	v_mul_f32_e32 v158, 0x3f317217, v154
	v_mul_f32_e32 v159, 0x3f317217, v155
	v_fma_f32 v156, v152, s78, -v156
	v_fma_f32 v157, v153, s78, -v157
	v_fma_f32 v158, v154, s78, -v158
	v_fma_f32 v159, v155, s78, -v159
	v_fmac_f32_e32 v156, 0x3377d1cf, v152
	v_fmac_f32_e32 v157, 0x3377d1cf, v153
	v_fmac_f32_e32 v158, 0x3377d1cf, v154
	v_fmac_f32_e32 v159, 0x3377d1cf, v155
	v_fmac_f32_e32 v156, 0x3f317217, v152
	v_fmac_f32_e32 v157, 0x3f317217, v153
	v_fmac_f32_e32 v158, 0x3f317217, v154
	v_fmac_f32_e32 v159, 0x3f317217, v155
	v_add_f32_e32 v140, v140, v156
	v_add_f32_e32 v141, v141, v157
	v_add_f32_e32 v142, v142, v158
	v_add_f32_e32 v143, v143, v159
	v_sub_f32_e32 v44, v44, v140
	v_sub_f32_e32 v45, v45, v141
	v_sub_f32_e32 v46, v46, v142
	v_sub_f32_e32 v47, v47, v143
	v_add_f32_e32 v152, v140, v141
	v_add_f32_e32 v153, v142, v143
	v_add_f32_e32 v122, v152, v153
	ds_bpermute_b32 v126, v114, v122
	v_mul_f32_e64 v152, |v40|, s67
	v_mul_f32_e64 v153, |v41|, s67
	v_mul_f32_e64 v154, |v42|, s67
	v_mul_f32_e64 v155, |v43|, s67
	v_exp_f32_e32 v152, v152
	v_exp_f32_e32 v153, v153
	v_exp_f32_e32 v154, v154
	v_exp_f32_e32 v155, v155
	v_max_f32_e32 v136, 0, v40
	v_max_f32_e32 v137, 0, v41
	v_max_f32_e32 v138, 0, v42
	v_max_f32_e32 v139, 0, v43
	v_add_f32_e32 v152, 1.0, v152
	v_add_f32_e32 v153, 1.0, v153
	v_add_f32_e32 v154, 1.0, v154
	v_add_f32_e32 v155, 1.0, v155
	v_log_f32_e32 v152, v152
	v_log_f32_e32 v153, v153
	v_log_f32_e32 v154, v154
	v_log_f32_e32 v155, v155
	s_nop 0
	v_mul_f32_e32 v156, 0x3f317217, v152
	v_mul_f32_e32 v157, 0x3f317217, v153
	v_mul_f32_e32 v158, 0x3f317217, v154
	v_mul_f32_e32 v159, 0x3f317217, v155
	v_fma_f32 v156, v152, s78, -v156
	v_fma_f32 v157, v153, s78, -v157
	v_fma_f32 v158, v154, s78, -v158
	v_fma_f32 v159, v155, s78, -v159
	v_fmac_f32_e32 v156, 0x3377d1cf, v152
	v_fmac_f32_e32 v157, 0x3377d1cf, v153
	v_fmac_f32_e32 v158, 0x3377d1cf, v154
	v_fmac_f32_e32 v159, 0x3377d1cf, v155
	v_fmac_f32_e32 v156, 0x3f317217, v152
	v_fmac_f32_e32 v157, 0x3f317217, v153
	v_fmac_f32_e32 v158, 0x3f317217, v154
	v_fmac_f32_e32 v159, 0x3f317217, v155
	v_add_f32_e32 v136, v136, v156
	v_add_f32_e32 v137, v137, v157
	v_add_f32_e32 v138, v138, v158
	v_add_f32_e32 v139, v139, v159
	v_sub_f32_e32 v40, v40, v136
	v_sub_f32_e32 v41, v41, v137
	v_sub_f32_e32 v42, v42, v138
	v_sub_f32_e32 v43, v43, v139
	v_add_f32_e32 v152, v136, v137
	v_add_f32_e32 v153, v138, v139
	v_add_f32_e32 v121, v152, v153
	ds_bpermute_b32 v125, v114, v121
	v_mul_f32_e64 v152, |v36|, s67
	v_mul_f32_e64 v153, |v37|, s67
	v_mul_f32_e64 v154, |v38|, s67
	v_mul_f32_e64 v155, |v39|, s67
	v_exp_f32_e32 v152, v152
	v_exp_f32_e32 v153, v153
	v_exp_f32_e32 v154, v154
	v_exp_f32_e32 v155, v155
	v_max_f32_e32 v132, 0, v36
	v_max_f32_e32 v133, 0, v37
	v_max_f32_e32 v134, 0, v38
	v_max_f32_e32 v135, 0, v39
	v_add_f32_e32 v152, 1.0, v152
	v_add_f32_e32 v153, 1.0, v153
	v_add_f32_e32 v154, 1.0, v154
	v_add_f32_e32 v155, 1.0, v155
	v_log_f32_e32 v152, v152
	v_log_f32_e32 v153, v153
	v_log_f32_e32 v154, v154
	v_log_f32_e32 v155, v155
	s_nop 0
	v_mul_f32_e32 v156, 0x3f317217, v152
	v_mul_f32_e32 v157, 0x3f317217, v153
	v_mul_f32_e32 v158, 0x3f317217, v154
	v_mul_f32_e32 v159, 0x3f317217, v155
	v_fma_f32 v156, v152, s78, -v156
	v_fma_f32 v157, v153, s78, -v157
	v_fma_f32 v158, v154, s78, -v158
	v_fma_f32 v159, v155, s78, -v159
	v_fmac_f32_e32 v156, 0x3377d1cf, v152
	v_fmac_f32_e32 v157, 0x3377d1cf, v153
	v_fmac_f32_e32 v158, 0x3377d1cf, v154
	v_fmac_f32_e32 v159, 0x3377d1cf, v155
	v_fmac_f32_e32 v156, 0x3f317217, v152
	v_fmac_f32_e32 v157, 0x3f317217, v153
	v_fmac_f32_e32 v158, 0x3f317217, v154
	v_fmac_f32_e32 v159, 0x3f317217, v155
	v_add_f32_e32 v132, v132, v156
	v_add_f32_e32 v133, v133, v157
	v_add_f32_e32 v134, v134, v158
	v_add_f32_e32 v135, v135, v159
	v_sub_f32_e32 v36, v36, v132
	v_sub_f32_e32 v37, v37, v133
	v_sub_f32_e32 v38, v38, v134
	v_sub_f32_e32 v39, v39, v135
	v_add_f32_e32 v152, v132, v133
	v_add_f32_e32 v153, v134, v135
	v_add_f32_e32 v120, v152, v153
	ds_bpermute_b32 v124, v114, v120
	v_mul_f32_e64 v152, |v32|, s67
	v_mul_f32_e64 v153, |v33|, s67
	v_mul_f32_e64 v154, |v34|, s67
	v_mul_f32_e64 v155, |v35|, s67
	v_exp_f32_e32 v152, v152
	v_exp_f32_e32 v153, v153
	v_exp_f32_e32 v154, v154
	v_exp_f32_e32 v155, v155
	v_max_f32_e32 v128, 0, v32
	v_max_f32_e32 v129, 0, v33
	v_max_f32_e32 v130, 0, v34
	v_max_f32_e32 v131, 0, v35
	v_add_f32_e32 v152, 1.0, v152
	v_add_f32_e32 v153, 1.0, v153
	v_add_f32_e32 v154, 1.0, v154
	v_add_f32_e32 v155, 1.0, v155
	v_log_f32_e32 v152, v152
	v_log_f32_e32 v153, v153
	v_log_f32_e32 v154, v154
	v_log_f32_e32 v155, v155
	s_nop 0
	v_mul_f32_e32 v156, 0x3f317217, v152
	v_mul_f32_e32 v157, 0x3f317217, v153
	v_mul_f32_e32 v158, 0x3f317217, v154
	v_mul_f32_e32 v159, 0x3f317217, v155
	v_fma_f32 v156, v152, s78, -v156
	v_fma_f32 v157, v153, s78, -v157
	v_fma_f32 v158, v154, s78, -v158
	v_fma_f32 v159, v155, s78, -v159
	v_fmac_f32_e32 v156, 0x3377d1cf, v152
	v_fmac_f32_e32 v157, 0x3377d1cf, v153
	v_fmac_f32_e32 v158, 0x3377d1cf, v154
	v_fmac_f32_e32 v159, 0x3377d1cf, v155
	v_fmac_f32_e32 v156, 0x3f317217, v152
	v_fmac_f32_e32 v157, 0x3f317217, v153
	v_fmac_f32_e32 v158, 0x3f317217, v154
	v_fmac_f32_e32 v159, 0x3f317217, v155
	v_add_f32_e32 v128, v128, v156
	v_add_f32_e32 v129, v129, v157
	v_add_f32_e32 v130, v130, v158
	v_add_f32_e32 v131, v131, v159
	v_sub_f32_e32 v32, v32, v128
	v_sub_f32_e32 v33, v33, v129
	v_sub_f32_e32 v34, v34, v130
	v_sub_f32_e32 v35, v35, v131
	v_add_f32_e32 v152, v128, v129
	v_add_f32_e32 v153, v130, v131
	v_add_f32_e32 v119, v152, v153
	ds_bpermute_b32 v123, v114, v119
	s_waitcnt lgkmcnt(3)
	v_and_b32_e32 v152, v116, v126
	v_add_f32_e32 v153, v122, v126
	v_sub_f32_e32 v199, v127, v152
	v_sub_f32_e32 v127, v127, v153
	v_mov_b32_e32 v159, v199
	v_sub_f32_e32 v158, v159, v143
	v_sub_f32_e32 v157, v158, v142
	v_sub_f32_e32 v156, v157, v141
	v_add_f32_e32 v44, v44, v156
	v_add_f32_e32 v45, v45, v157
	v_add_f32_e32 v46, v46, v158
	v_add_f32_e32 v47, v47, v159
	v_mul_f32_e32 v44, 0x3fb8aa3b, v44
	v_mul_f32_e32 v45, 0x3fb8aa3b, v45
	v_mul_f32_e32 v46, 0x3fb8aa3b, v46
	v_mul_f32_e32 v47, 0x3fb8aa3b, v47
	v_exp_f32_e32 v44, v44
	v_exp_f32_e32 v45, v45
	v_exp_f32_e32 v46, v46
	v_exp_f32_e32 v47, v47
	s_waitcnt lgkmcnt(2)
	v_and_b32_e32 v152, v116, v125
	v_add_f32_e32 v153, v121, v125
	v_sub_f32_e32 v199, v127, v152
	v_sub_f32_e32 v127, v127, v153
	v_mov_b32_e32 v159, v199
	v_sub_f32_e32 v158, v159, v139
	v_sub_f32_e32 v157, v158, v138
	v_sub_f32_e32 v156, v157, v137
	v_add_f32_e32 v40, v40, v156
	v_add_f32_e32 v41, v41, v157
	v_add_f32_e32 v42, v42, v158
	v_add_f32_e32 v43, v43, v159
	v_mul_f32_e32 v40, 0x3fb8aa3b, v40
	v_mul_f32_e32 v41, 0x3fb8aa3b, v41
	v_mul_f32_e32 v42, 0x3fb8aa3b, v42
	v_mul_f32_e32 v43, 0x3fb8aa3b, v43
	v_exp_f32_e32 v40, v40
	v_exp_f32_e32 v41, v41
	v_exp_f32_e32 v42, v42
	v_exp_f32_e32 v43, v43
	s_waitcnt lgkmcnt(1)
	v_and_b32_e32 v152, v116, v124
	v_add_f32_e32 v153, v120, v124
	v_sub_f32_e32 v199, v127, v152
	v_sub_f32_e32 v127, v127, v153
	v_mov_b32_e32 v159, v199
	v_sub_f32_e32 v158, v159, v135
	v_sub_f32_e32 v157, v158, v134
	v_sub_f32_e32 v156, v157, v133
	v_add_f32_e32 v36, v36, v156
	v_add_f32_e32 v37, v37, v157
	v_add_f32_e32 v38, v38, v158
	v_add_f32_e32 v39, v39, v159
	v_mul_f32_e32 v36, 0x3fb8aa3b, v36
	v_mul_f32_e32 v37, 0x3fb8aa3b, v37
	v_mul_f32_e32 v38, 0x3fb8aa3b, v38
	v_mul_f32_e32 v39, 0x3fb8aa3b, v39
	v_exp_f32_e32 v36, v36
	v_exp_f32_e32 v37, v37
	v_exp_f32_e32 v38, v38
	v_exp_f32_e32 v39, v39
	s_waitcnt lgkmcnt(0)
	v_and_b32_e32 v152, v116, v123
	v_add_f32_e32 v153, v119, v123
	v_sub_f32_e32 v199, v127, v152
	v_sub_f32_e32 v127, v127, v153
	v_mov_b32_e32 v159, v199
	v_sub_f32_e32 v158, v159, v131
	v_sub_f32_e32 v157, v158, v130
	v_sub_f32_e32 v156, v157, v129
	v_add_f32_e32 v32, v32, v156
	v_add_f32_e32 v33, v33, v157
	v_add_f32_e32 v34, v34, v158
	v_add_f32_e32 v35, v35, v159
	v_mul_f32_e32 v32, 0x3fb8aa3b, v32
	v_mul_f32_e32 v33, 0x3fb8aa3b, v33
	v_mul_f32_e32 v34, 0x3fb8aa3b, v34
	v_mul_f32_e32 v35, 0x3fb8aa3b, v35
	v_exp_f32_e32 v32, v32
	v_exp_f32_e32 v33, v33
	v_exp_f32_e32 v34, v34
	v_exp_f32_e32 v35, v35
	v_cvt_pk_bf16_f32 v144, v32, v33
	v_cvt_pk_bf16_f32 v145, v34, v35
	v_cvt_pk_bf16_f32 v146, v36, v37
	v_cvt_pk_bf16_f32 v147, v38, v39
	v_cvt_pk_bf16_f32 v148, v40, v41
	v_cvt_pk_bf16_f32 v149, v42, v43
	v_cvt_pk_bf16_f32 v150, v44, v45
	v_cvt_pk_bf16_f32 v151, v46, v47
	v_cmp_gt_f32_e32 vcc, s82, v127
	s_waitcnt vmcnt(0)
	v_mfma_f32_32x32x16_bf16 v[16:31], v[98:101], v[144:147], v[16:31]
	v_mfma_f32_32x32x16_bf16 v[0:15], v[102:105], v[144:147], v[0:15]
	v_mfma_f32_32x32x16_bf16 v[16:31], v[106:109], v[148:151], v[16:31]
	v_mfma_f32_32x32x16_bf16 v[0:15], v[110:113], v[148:151], v[0:15]
	v_mov_b64_e32 v[66:67], v[82:83]
	v_mov_b64_e32 v[68:69], v[84:85]
	v_mov_b64_e32 v[70:71], v[86:87]
	v_mov_b64_e32 v[72:73], v[88:89]
	v_mov_b64_e32 v[74:75], v[90:91]
	v_mov_b64_e32 v[76:77], v[92:93]
	v_mov_b64_e32 v[78:79], v[94:95]
	v_mov_b64_e32 v[80:81], v[96:97]
	s_cmp_eq_u64 vcc, exec
	s_cselect_b32 s0, 1, 0
	s_cmp_eq_u32 s12, 0
	s_cselect_b32 s1, 1, 0
	s_or_b32 s0, s0, s1
	s_sub_i32 s12, s12, 1
	s_cmp_lg_u32 s0, 0
	s_cbranch_scc0 .Lsb_loop
.Lsb_done:
	v_readfirstlane_b32 s2, v118
	s_nop 7
	s_nop 2
	global_store_dwordx4 v[160:161], v[16:19], off
	global_store_dwordx4 v[160:161], v[20:23], off offset:32
	global_store_dwordx4 v[160:161], v[24:27], off offset:64
	global_store_dwordx4 v[160:161], v[28:31], off offset:96
	global_store_dwordx4 v[160:161], v[0:3], off offset:128
	global_store_dwordx4 v[160:161], v[4:7], off offset:160
	global_store_dwordx4 v[160:161], v[8:11], off offset:192
	global_store_dwordx4 v[160:161], v[12:15], off offset:224
	s_cmpk_gt_i32 s2, 0x1ff
	s_cbranch_scc0 .LBB0_354
